# RG-LRU tile loops beside the delta recurrence: gate-branch loads hoisted to tile start; RG_SPLIT 7->4 (more RG-LRU tiles hidden under the recurrence)
# speedup vs baseline: 1.0037x; 1.0037x over previous
; #define RG_RAW_LOAD(tile_) do { _Pragma("unroll") for (int i = 0; i < 5; ++i) { const int q = tid + 512 * i, row = q >> 4, c16 = q & 15, tl = (tile_) * 128 - 3 + row; \
;         pre[i] = (q < 131 * 16 && tl >= 0) ? *(const u32x4*)(XR + ((size_t)b * SEQ + tl) * D + cb0 + c16 * 8) : (u32x4){0u, 0u, 0u, 0u}; } } while (0)
; #define RG_RAW_STORE() do { _Pragma("unroll") for (int i = 0; i < 5; ++i) { const int q = tid + 512 * i; if (q < 131 * 16) *(LAS u32x4*)(rawt + (q >> 4) * 136 + (q & 15) * 8) = pre[i]; } } while (0)
; __device__ __forceinline__ void rglru_task(const Params& P, LAS unsigned char* lds, int b, int n, int qd, int tid, int t0, int t1) {
;     ...
;     if (prompt) { RG_RAW_LOAD(t0); RG_RAW_STORE(); }
;     __syncthreads();
;     const int ntiles = t1;
;     for (int tile = t0; tile < ntiles; ++tile) {
;         const int row0 = prompt ? b * SEQ + tile * 128 : MPR;
;         if (prompt && tile + 1 < ntiles) RG_RAW_LOAD(tile + 1);
.LBB0_1296:
	s_or_b64 exec, exec, s[4:5]
	s_add_i32 s61, s61, 1
	s_cmp_eq_u32 s61, 4
	s_cbranch_scc1 .LBB0_1407
.LBB0_1297:
	s_lshl_b32 s64, s61, 7
	s_cmp_lt_u32 s61, 3
	s_cselect_b64 s[4:5], -1, 0
	s_and_b64 s[68:69], s[58:59], s[4:5]
	s_andn2_b64 vcc, exec, s[68:69]
	s_cbranch_vccnz .LBB0_1309
	s_or_b32 s6, s64, 0x7d
	v_add_u32_e32 v0, s6, v149
	s_waitcnt vmcnt(0)
	v_mov_b32_e32 v50, v68
	v_mov_b32_e32 v51, v68
	v_cmp_lt_i32_e32 vcc, -1, v0
	v_mov_b32_e32 v48, v68
	v_mov_b32_e32 v49, v68
	v_mov_b64_e32 v[54:55], v[50:51]
	s_and_b64 s[52:53], s[10:11], vcc
	v_mov_b64_e32 v[52:53], v[48:49]
	s_and_saveexec_b64 s[4:5], s[52:53]
	s_cbranch_execz .LBB0_1300
	v_mov_b32_e32 v1, v68
	v_lshlrev_b64 v[0:1], 11, v[0:1]
	v_lshl_add_u64 v[0:1], v[74:75], 0, v[0:1]
	global_load_dwordx4 v[52:55], v[0:1], off

; #define RG_RAW_LOAD(tile_) do { _Pragma("unroll") for (int i = 0; i < 5; ++i) { const int q = tid + 512 * i, row = q >> 4, c16 = q & 15, tl = (tile_) * 128 - 3 + row; \
;         pre[i] = (q < 131 * 16 && tl >= 0) ? *(const u32x4*)(XR + ((size_t)b * SEQ + tl) * D + cb0 + c16 * 8) : (u32x4){0u, 0u, 0u, 0u}; } } while (0)
; #define RG_RAW_STORE() do { _Pragma("unroll") for (int i = 0; i < 5; ++i) { const int q = tid + 512 * i; if (q < 131 * 16) *(LAS u32x4*)(rawt + (q >> 4) * 136 + (q & 15) * 8) = pre[i]; } } while (0)
; __device__ __forceinline__ void rglru_task(const Params& P, LAS unsigned char* lds, int b, int n, int qd, int tid, int t0, int t1) {
;     ...
;     if (prompt) { RG_RAW_LOAD(t0); RG_RAW_STORE(); }
.LBB0_1634:
	s_or_b64 exec, exec, s[12:13]
	s_lshl_b64 s[8:9], s[6:7], 22
	s_add_u32 s8, s10, s8
	s_addc_u32 s9, s11, s9
	s_lshl_b32 s10, s18, 1
	v_lshlrev_b32_e32 v2, 3, v0
	s_add_u32 s8, s8, s10
	v_and_b32_e32 v2, 0x78, v2
	s_addc_u32 s9, s9, 0
	v_lshlrev_b32_e32 v48, 1, v2
	v_lshl_add_u64 v[4:5], s[8:9], 0, v[48:49]
	s_mov_b64 s[8:9], 0x5040000
	v_lshl_add_u64 v[74:75], v[4:5], 0, s[8:9]
	v_ashrrev_i32_e32 v79, 4, v0
	s_movk_i32 s8, 0x830
	s_movk_i32 s12, 0xfc82
	v_cmp_gt_i32_e64 s[8:9], s8, v0
	v_cmp_lt_i32_e64 s[10:11], s12, v79
	s_and_b64 s[14:15], s[8:9], s[10:11]
	v_mov_b32_e32 v48, v49
	v_mov_b32_e32 v50, v49
	v_mov_b32_e32 v51, v49
	s_and_saveexec_b64 s[10:11], s[14:15]
	s_cbranch_execz .LBB0_1636
	v_add_u32_e32 v4, 0x1fd, v79
	v_mov_b32_e32 v5, 0
	v_lshlrev_b64 v[4:5], 11, v[4:5]
	v_lshl_add_u64 v[4:5], v[74:75], 0, v[4:5]
	global_load_dwordx4 v[48:51], v[4:5], off
.LBB0_1636:
	s_or_b64 exec, exec, s[10:11]
	v_add_u32_e32 v3, 0x200, v0
	v_mov_b32_e32 v56, 0
	v_ashrrev_i32_e32 v80, 4, v3
	s_movk_i32 s10, 0x630
	v_mov_b32_e32 v57, v56
	v_cmp_gt_i32_e64 s[10:11], s10, v0
	v_cmp_lt_i32_e64 s[12:13], s12, v80
	v_mov_b32_e32 v58, v56
	v_mov_b32_e32 v59, v56
	v_mov_b64_e32 v[52:53], v[56:57]
	s_and_b64 s[14:15], s[10:11], s[12:13]
	v_mov_b64_e32 v[54:55], v[58:59]
	s_and_saveexec_b64 s[12:13], s[14:15]
	s_cbranch_execz .LBB0_1638
	v_add_u32_e32 v4, 0x1fd, v80
	v_mov_b32_e32 v5, v56
	v_lshlrev_b64 v[4:5], 11, v[4:5]
	v_lshl_add_u64 v[4:5], v[74:75], 0, v[4:5]
	global_load_dwordx4 v[52:55], v[4:5], off
.LBB0_1638:
	s_or_b64 exec, exec, s[12:13]
	v_add_u32_e32 v3, 0x400, v0
	v_ashrrev_i32_e32 v81, 4, v3
	s_movk_i32 s12, 0x430
	s_movk_i32 s16, 0xfc82
	v_cmp_gt_i32_e64 s[12:13], s12, v0
	v_cmp_lt_i32_e64 s[14:15], s16, v81
	s_and_b64 s[18:19], s[12:13], s[14:15]
	s_and_saveexec_b64 s[14:15], s[18:19]
	s_cbranch_execz .LBB0_1640
	v_add_u32_e32 v4, 0x1fd, v81
	v_mov_b32_e32 v5, 0
	v_lshlrev_b64 v[4:5], 11, v[4:5]
	v_lshl_add_u64 v[4:5], v[74:75], 0, v[4:5]
	global_load_dwordx4 v[56:59], v[4:5], off
.LBB0_1640:
	s_or_b64 exec, exec, s[14:15]
	v_add_u32_e32 v3, 0x600, v0
	v_mov_b32_e32 v64, 0
	v_ashrrev_i32_e32 v82, 4, v3
	s_movk_i32 s14, 0x230
	v_mov_b32_e32 v65, v64
	v_cmp_gt_i32_e64 s[14:15], s14, v0
	v_cmp_lt_i32_e64 s[16:17], s16, v82
	v_mov_b32_e32 v66, v64
	v_mov_b32_e32 v67, v64
	v_mov_b64_e32 v[60:61], v[64:65]
	s_and_b64 s[18:19], s[14:15], s[16:17]
	v_mov_b64_e32 v[62:63], v[66:67]
	s_and_saveexec_b64 s[16:17], s[18:19]
	s_cbranch_execz .LBB0_1642
	v_add_u32_e32 v4, 0x1fd, v82
	v_mov_b32_e32 v5, 0
	v_lshlrev_b64 v[4:5], 11, v[4:5]
	v_lshl_add_u64 v[4:5], v[74:75], 0, v[4:5]
	global_load_dwordx4 v[60:63], v[4:5], off
.LBB0_1642:
	s_or_b64 exec, exec, s[16:17]
	v_add_u32_e32 v3, 0x800, v0
	v_ashrrev_i32_e32 v83, 4, v3
	s_movk_i32 s18, 0xfc82
	v_cmp_gt_i32_e64 s[16:17], 48, v0
	v_cmp_lt_i32_e64 s[18:19], s18, v83
	s_and_b64 s[20:21], s[16:17], s[18:19]
	v_mov_b32_e32 v65, 0
	v_mov_b32_e32 v66, 0
	v_mov_b32_e32 v67, 0
	s_and_saveexec_b64 s[18:19], s[20:21]
	s_cbranch_execz .LBB0_1644
	v_add_u32_e32 v4, 0x1fd, v83
	v_mov_b32_e32 v5, 0
	v_lshlrev_b64 v[4:5], 11, v[4:5]
	v_lshl_add_u64 v[4:5], v[74:75], 0, v[4:5]
	global_load_dwordx4 v[64:67], v[4:5], off

; #define LAS __attribute__((address_space(3)))
; __device__ __forceinline__ float softplus_f(float x) { return x > 20.f ? x : log1pf(__expf(x)); }
; __device__ __forceinline__ unsigned char* karg_ws() { return *(volatile KAS ucptr_t*)((const KAS char*)__builtin_amdgcn_kernarg_segment_ptr() + 264); }
; #define INP(k) karg_in(k)
; #define RG_RAW_LOAD(tile_) do { _Pragma("unroll") for (int i = 0; i < 5; ++i) { const int q = tid + 512 * i, row = q >> 4, c16 = q & 15, tl = (tile_) * 128 - 3 + row; \
;         pre[i] = (q < 131 * 16 && tl >= 0) ? *(const u32x4*)(XR + ((size_t)b * SEQ + tl) * D + cb0 + c16 * 8) : (u32x4){0u, 0u, 0u, 0u}; } } while (0)
; #define lane opq(lane_now())
; __device__ __forceinline__ void rglru_task(const Params& P, LAS unsigned char* lds, int b, int n, int qd, int tid, int t0, int t1) {
;     const int lane = tid & 63, wave = tid >> 6;
;     LAS bf16* xcA = (LAS bf16*)lds;
;     LAS float* xcf = (LAS float*)(lds + 34816);
;     LAS float* rb = (LAS float*)(lds + 51200);
;     LAS float* ib = (LAS float*)(lds + 67584);
;     LAS float* segA = (LAS float*)(lds + 83968);
;     LAS float* segB = (LAS float*)(lds + 86016);
;     LAS float* hc = (LAS float*)(lds + 88064);
;     LAS float* cw = (LAS float*)(lds + 88192);
;     LAS bf16* rawt = (LAS bf16*)(lds + 90752);
;     bf16* XR = (bf16*)(karg_ws() + WS_Z); bf16* GR = (bf16*)(karg_ws() + WS_Z + ZB);
;     const bf16* WRG = (const bf16*)(karg_ws() + WS_WRG);
;     const int cb0 = n * 128, oc0 = cb0 + qd * 32;
;     const bool prompt = b >= 0;
;     for (int i = tid; i < 640; i += NTHR) cw[i] = i < 512 ? INP(15)[(size_t)(i >> 7) * D + cb0 + (i & 127)] : INP(16)[cb0 + (i - 512)];
;     if (tid < 32) hc[tid] = t0 > 0 ? ((const float*)(karg_ws() + WS_HCARRY))[(size_t)b * D + oc0 + tid] : 0.f;
;     const int tb = wave & 3, cbk = wave >> 2;
;     bf16x8 Bf[8];
;     { const bf16* wrow = WRG + (size_t)(n * 256 + cbk * 128 + qd * 32 + (lane & 31)) * 128 + (lane >> 5) * 8;
; #pragma unroll
;       for (int ks = 0; ks < 8; ++ks) Bf[ks] = *(const bf16x8*)(wrow + ks * 16); }
;     const float gbias = INP(cbk ? 20 : 18)[oc0 + (lane & 31)];
;     const int ch = tid & 31, seg = tid >> 5;
;     const float sp = softplus_f(-INP(21)[oc0 + ch]);
;     float hlast = 0.f;
;     u32x4 pre[5];
;     ...
;     if (prompt) { RG_RAW_LOAD(t0); RG_RAW_STORE(); }
;     __syncthreads();
;     const int ntiles = t1;
.LBB0_1651:
	s_or_b64 exec, exec, s[18:19]
	v_lshrrev_b32_e32 v4, 1, v0
	v_and_b32_e32 v10, 0x60, v4
	s_add_i32 s20, 0, 0xc800
	s_lshl_b32 s65, s6, 11
	v_or_b32_e32 v4, v10, v72
	s_add_i32 s57, 0, 0x10800
	v_mov_b32_e32 v5, s20
	s_add_i32 s58, 0, 0x14800
	s_add_i32 s59, 0, 0x15000
	s_add_i32 s63, 0, 0x15800
	s_lshl_b32 s20, s64, 1
	v_mul_u32_u24_e32 v11, 0x110, v4
	v_mov_b32_e32 v4, s57
	v_mov_b32_e32 v68, 0
	s_add_u32 s4, s4, s20
	v_cndmask_b32_e32 v12, v4, v5, vcc
	s_addc_u32 s5, s5, 0
	v_lshlrev_b32_e32 v4, 1, v72
	v_mov_b32_e32 v5, v68
	v_lshlrev_b32_e32 v13, 2, v72
	v_lshl_add_u64 v[4:5], s[4:5], 0, v[4:5]
	s_mov_b64 s[4:5], 0x7080000
	v_lshl_add_u64 v[76:77], v[4:5], 0, s[4:5]
	v_or_b32_e32 v4, 0x80, v13
	v_add_u32_e32 v89, s58, v4
	v_add_u32_e32 v90, s59, v4
	v_or_b32_e32 v4, 0x100, v13
	v_add_u32_e32 v91, s58, v4
	v_add_u32_e32 v92, s59, v4
	v_or_b32_e32 v4, 0x180, v13
	v_add_u32_e32 v93, s58, v4
	v_add_u32_e32 v94, s59, v4
	v_or_b32_e32 v4, 0x200, v13
	v_add_u32_e32 v95, s58, v4
	v_add_u32_e32 v96, s59, v4
	v_or_b32_e32 v4, 0x280, v13
	v_add_u32_e32 v97, s58, v4
	v_add_u32_e32 v98, s59, v4
	v_or_b32_e32 v4, 0x300, v13
	v_add_u32_e32 v99, s58, v4
	v_add_u32_e32 v100, s59, v4
	v_or_b32_e32 v4, 0x380, v13
	v_add_u32_e32 v101, s58, v4
	v_add_u32_e32 v102, s59, v4
	v_or_b32_e32 v4, 0x400, v13
	v_add_u32_e32 v103, s58, v4
	v_add_u32_e32 v104, s59, v4
	v_or_b32_e32 v4, 0x480, v13
	v_add_u32_e32 v105, s58, v4
	v_add_u32_e32 v106, s59, v4
	v_or_b32_e32 v4, 0x500, v13
	v_add_u32_e32 v107, s58, v4
	v_add_u32_e32 v108, s59, v4
	v_or_b32_e32 v4, 0x580, v13
	v_add_u32_e32 v109, s58, v4
	v_add_u32_e32 v110, s59, v4
	v_or_b32_e32 v4, 0x600, v13
	v_ashrrev_i32_e32 v6, 5, v0
	v_add_u32_e32 v111, s58, v4
	v_add_u32_e32 v112, s59, v4
	v_or_b32_e32 v4, 0x680, v13
	v_lshlrev_b32_e32 v85, 3, v6
	v_add_u32_e32 v113, s58, v4
	v_add_u32_e32 v114, s59, v4
	v_or_b32_e32 v4, 0x700, v13
	v_add_u32_e32 v115, s58, v4
	v_add_u32_e32 v116, s59, v4
	v_or_b32_e32 v119, 1, v85
	v_lshl_or_b32 v4, v6, 10, v13
	v_or_b32_e32 v120, 2, v85
	v_add_u32_e32 v126, 0, v4
	v_add_u32_e32 v127, s57, v4
	v_lshl_or_b32 v4, v119, 7, v13
	v_or_b32_e32 v121, 3, v85
	v_add_u32_e32 v128, 0, v4
	v_add_u32_e32 v129, s57, v4
	v_lshl_or_b32 v4, v120, 7, v13
	v_or_b32_e32 v122, 4, v85
	v_add_u32_e32 v130, 0, v4
	v_add_u32_e32 v131, s57, v4
	v_lshl_or_b32 v4, v121, 7, v13
	v_or_b32_e32 v123, 5, v85
	v_add_u32_e32 v132, 0, v4
	v_add_u32_e32 v133, s57, v4
	v_lshl_or_b32 v4, v122, 7, v13
	v_or_b32_e32 v124, 6, v85
	v_add_u32_e32 v134, 0, v4
	v_add_u32_e32 v135, s57, v4
	v_lshl_or_b32 v4, v123, 7, v13
	v_ashrrev_i32_e32 v7, 2, v0
	v_and_b32_e32 v8, 3, v0
	v_lshlrev_b32_e32 v0, 2, v0
	v_or_b32_e32 v125, 7, v85
	v_add_u32_e32 v136, 0, v4
	v_add_u32_e32 v137, s57, v4
	v_lshl_or_b32 v4, v124, 7, v13
	v_add_u32_e32 v86, s58, v0
	v_add_u32_e32 v87, s59, v0
	v_lshlrev_b32_e32 v0, 9, v1
	v_add_u32_e32 v138, 0, v4
	v_add_u32_e32 v139, s57, v4
	v_lshl_or_b32 v4, v125, 7, v13
	v_lshl_add_u32 v3, v3, 1, 0
	v_mul_lo_u32 v9, v7, s54
	v_cmp_eq_u32_e64 s[20:21], 15, v6
	v_lshlrev_b32_e32 v1, 7, v10
	v_add3_u32 v0, v12, v13, v0
	v_cmp_lt_i32_e64 s[22:23], 0, v6
	v_cmp_lt_i32_e64 s[24:25], 1, v6
	v_cmp_lt_i32_e64 s[26:27], 2, v6
	v_cmp_lt_i32_e64 s[28:29], 3, v6
	v_cmp_lt_i32_e64 s[30:31], 4, v6
	v_cmp_lt_i32_e64 s[34:35], 5, v6
	v_cmp_lt_i32_e64 s[36:37], 6, v6
	v_cmp_lt_i32_e64 s[38:39], 7, v6
	v_cmp_lt_i32_e64 s[40:41], 8, v6
	v_cmp_lt_i32_e64 s[42:43], 9, v6
	v_cmp_lt_i32_e64 s[44:45], 10, v6
	v_cmp_lt_i32_e64 s[46:47], 11, v6
	v_cmp_lt_i32_e64 s[48:49], 12, v6
	v_cmp_lt_i32_e64 s[50:51], 13, v6
	v_cmp_lt_i32_e64 s[52:53], 14, v6
	v_add_u32_e32 v140, 0, v4
	v_add_u32_e32 v141, s57, v4
	v_mul_lo_u32 v4, v79, s54
	v_mul_lo_u32 v5, v80, s54
	v_mul_lo_u32 v6, v81, s54
	v_mul_lo_u32 v10, v82, s54
	v_mov_b32_e32 v12, 0x8800
	v_cmp_eq_u32_e64 s[18:19], s3, v8
	v_add_u32_e32 v88, s63, v13
	s_mov_b32 s68, 4
	v_add_u32_e32 v117, s59, v13
	v_add_u32_e32 v118, s58, v13
	v_lshlrev_b32_e32 v142, 7, v8
	v_lshl_add_u32 v143, v7, 7, v12
	v_lshl_add_u32 v144, v8, 6, v9
	v_add_u32_e32 v145, v3, v11
	v_add_u32_e32 v146, v0, v1
	v_mov_b32_e32 v147, 0x3c088889
	s_mov_b32 s66, 0xbe99999a
	v_add_u32_e32 v148, v2, v4
	v_add_u32_e32 v149, v2, v5
	v_add_u32_e32 v150, v2, v6
	v_add_u32_e32 v151, v2, v10
	s_waitcnt lgkmcnt(0)
	s_barrier
	s_branch .LBB0_1653

; #define INP(k) karg_in(k)
; #define RG_RAW_LOAD(tile_) do { _Pragma("unroll") for (int i = 0; i < 5; ++i) { const int q = tid + 512 * i, row = q >> 4, c16 = q & 15, tl = (tile_) * 128 - 3 + row; \
;         pre[i] = (q < 131 * 16 && tl >= 0) ? *(const u32x4*)(XR + ((size_t)b * SEQ + tl) * D + cb0 + c16 * 8) : (u32x4){0u, 0u, 0u, 0u}; } } while (0)
; __device__ __forceinline__ void rglru_task(const Params& P, LAS unsigned char* lds, int b, int n, int qd, int tid, int t0, int t1) {
;     ...
;     for (int tile = t0; tile < ntiles; ++tile) {
;         const int row0 = prompt ? b * SEQ + tile * 128 : MPR;
;         if (prompt && tile + 1 < ntiles) RG_RAW_LOAD(tile + 1);
;     ...
;         { float gr[8], h0v[8];
; #pragma unroll
;           for (int e = 0; e < 8; ++e) { const int t = seg * 8 + e; gr[e] = bf2f(GR[(size_t)(row0 + t) * D + oc0 + ch]); h0v[e] = prompt ? 0.f : INP(4)[(size_t)t * D + oc0 + ch]; }
.LBB0_1665:
	s_lshl_b32 s32, s68, 7
	s_add_i32 s32, s32, s65
	v_add_u32_e32 v196, s32, v85
	v_ashrrev_i32_e32 v197, 31, v196
	v_add_u32_e32 v198, s32, v119
	v_add_u32_e32 v200, s32, v120
	v_add_u32_e32 v202, s32, v121
	v_add_u32_e32 v204, s32, v122
	v_add_u32_e32 v206, s32, v123
	v_add_u32_e32 v208, s32, v124
	v_add_u32_e32 v210, s32, v125
	v_lshlrev_b64 v[196:197], 11, v[196:197]
	v_ashrrev_i32_e32 v199, 31, v198
	v_ashrrev_i32_e32 v201, 31, v200
	v_ashrrev_i32_e32 v203, 31, v202
	v_ashrrev_i32_e32 v205, 31, v204
	v_ashrrev_i32_e32 v207, 31, v206
	v_ashrrev_i32_e32 v209, 31, v208
	v_ashrrev_i32_e32 v211, 31, v210
	v_lshl_add_u64 v[196:197], v[76:77], 0, v[196:197]
	v_lshlrev_b64 v[198:199], 11, v[198:199]
	v_lshlrev_b64 v[200:201], 11, v[200:201]
	v_lshlrev_b64 v[202:203], 11, v[202:203]
	v_lshlrev_b64 v[204:205], 11, v[204:205]
	v_lshlrev_b64 v[206:207], 11, v[206:207]
	v_lshlrev_b64 v[208:209], 11, v[208:209]
	v_lshlrev_b64 v[210:211], 11, v[210:211]
	v_lshl_add_u64 v[198:199], v[76:77], 0, v[198:199]
	v_lshl_add_u64 v[200:201], v[76:77], 0, v[200:201]
	v_lshl_add_u64 v[202:203], v[76:77], 0, v[202:203]
	v_lshl_add_u64 v[204:205], v[76:77], 0, v[204:205]
	v_lshl_add_u64 v[206:207], v[76:77], 0, v[206:207]
	v_lshl_add_u64 v[208:209], v[76:77], 0, v[208:209]
	v_lshl_add_u64 v[210:211], v[76:77], 0, v[210:211]
	global_load_ushort v212, v[196:197], off
	global_load_ushort v213, v[198:199], off
	global_load_ushort v214, v[200:201], off
	global_load_ushort v215, v[202:203], off
	global_load_ushort v216, v[204:205], off
	global_load_ushort v217, v[206:207], off
	global_load_ushort v218, v[208:209], off
	global_load_ushort v219, v[210:211], off
	s_mov_b32 s69, 4
	v_mov_b32_e32 v8, v144
	v_mov_b32_e32 v9, v143
	v_mov_b32_e32 v10, v142
	s_branch .LBB0_1667

; __device__ __forceinline__ unsigned f2bf(float f) { return pk2(f, f) & 0xffffu; }
; __device__ __forceinline__ float* karg_out() { return *(volatile KAS fptr_t*)((const KAS char*)__builtin_amdgcn_kernarg_segment_ptr() + 256); }
; #define INP(k) karg_in(k)
; __device__ __forceinline__ void rglru_task(const Params& P, LAS unsigned char* lds, int b, int n, int qd, int tid, int t0, int t1) {
;     ...
;         float hin = 0.f;
;         if (prompt) {
;             segA[seg * 32 + ch] = Aacc; segB[seg * 32 + ch] = h;
;             __syncthreads();
;             hin = hc[ch];
;             float sa[15], sb[15];
; #pragma unroll
;             for (int s = 0; s < 15; ++s) { sa[s] = segA[s * 32 + ch]; sb[s] = segB[s * 32 + ch]; }
; #pragma unroll
;             for (int s = 0; s < 15; ++s) hin = s < seg ? sa[s] * hin + sb[s] : hin;
;         }
;         h = hin;
;         { float gr[8], h0v[8];
; #pragma unroll
;           for (int e = 0; e < 8; ++e) { const int t = seg * 8 + e; gr[e] = bf2f(GR[(size_t)(row0 + t) * D + oc0 + ch]); h0v[e] = prompt ? 0.f : INP(4)[(size_t)t * D + oc0 + ch]; }
; #pragma unroll
;           for (int e = 0; e < 8; ++e) { const int t = seg * 8 + e;
;               const float a = rb[t * 32 + ch], bt = ib[t * 32 + ch];
;               if (prompt) h = a * h + bt; else h = a * h0v[e] + bt;
;               GR[(size_t)(row0 + t) * D + oc0 + ch] = (bf16)f2bf(h * gr[e]);
;               if (!prompt) { karg_out()[O_HS + (size_t)t * D + oc0 + ch] = h;
;                   const float* cs = INP(5) + (size_t)t * 3 * D + oc0 + ch; float* co = karg_out() + O_CRS + (size_t)t * 3 * D + oc0 + ch;
;                   co[0] = cs[D]; co[D] = cs[2 * D]; co[2 * D] = bf2f(XR[(size_t)(MPR + t) * D + oc0 + ch]); }
;           } }
;         hlast = h;
.LBB0_1675:
	s_or_b64 exec, exec, s[4:5]
	s_waitcnt lgkmcnt(14)
	v_fmac_f32_e32 v14, v161, v0
	v_cndmask_b32_e64 v0, v0, v14, s[24:25]
	v_fmac_f32_e32 v15, v1, v0
	v_cndmask_b32_e64 v0, v0, v15, s[26:27]
	v_fmac_f32_e32 v69, v2, v0
	v_cndmask_b32_e64 v0, v0, v69, s[28:29]
	v_fmac_f32_e32 v70, v3, v0
	v_cndmask_b32_e64 v0, v0, v70, s[30:31]
	v_fmac_f32_e32 v71, v4, v0
	v_cndmask_b32_e64 v0, v0, v71, s[34:35]
	v_fmac_f32_e32 v152, v5, v0
	v_cndmask_b32_e64 v0, v0, v152, s[36:37]
	v_fmac_f32_e32 v153, v6, v0
	v_cndmask_b32_e64 v0, v0, v153, s[38:39]
	s_waitcnt lgkmcnt(12)
	v_fmac_f32_e32 v154, v7, v0
	v_cndmask_b32_e64 v0, v0, v154, s[40:41]
	s_waitcnt lgkmcnt(10)
	v_fmac_f32_e32 v155, v8, v0
	v_cndmask_b32_e64 v0, v0, v155, s[42:43]
	s_waitcnt lgkmcnt(8)
	v_fmac_f32_e32 v156, v9, v0
	v_cndmask_b32_e64 v0, v0, v156, s[44:45]
	s_waitcnt lgkmcnt(6)
	v_fmac_f32_e32 v157, v10, v0
	v_cndmask_b32_e64 v0, v0, v157, s[46:47]
	s_waitcnt lgkmcnt(4)
	v_fmac_f32_e32 v158, v11, v0
	v_cndmask_b32_e64 v0, v0, v158, s[48:49]
	s_waitcnt lgkmcnt(2)
	v_fmac_f32_e32 v159, v12, v0
	v_cndmask_b32_e64 v0, v0, v159, s[50:51]
	s_waitcnt lgkmcnt(0)
	v_fmac_f32_e32 v160, v13, v0
	ds_read_b32 v161, v126 offset:51200
	ds_read_b32 v188, v127
	ds_read_b32 v189, v128 offset:51200
	ds_read_b32 v190, v129
	ds_read_b32 v191, v130 offset:51200
	ds_read_b32 v192, v131
	ds_read_b32 v193, v132 offset:51200
	ds_read_b32 v194, v133
	v_cndmask_b32_e64 v0, v0, v160, s[52:53]
	s_waitcnt lgkmcnt(6)
	v_fmac_f32_e32 v188, v161, v0
	s_waitcnt lgkmcnt(4)
	v_fmac_f32_e32 v190, v189, v188
	s_waitcnt lgkmcnt(2)
	v_fmac_f32_e32 v192, v191, v190
	s_waitcnt lgkmcnt(0)
	v_fmac_f32_e32 v194, v193, v192
	s_andn2_b64 vcc, exec, s[54:55]
	s_waitcnt vmcnt(7)
	v_lshlrev_b32_e32 v0, 16, v212
	v_mul_f32_e32 v0, v188, v0
	s_waitcnt vmcnt(6)
	v_lshlrev_b32_e32 v1, 16, v213
	v_cvt_pk_bf16_f32 v0, v0, s0
	global_store_short v[196:197], v0, off
	v_mul_f32_e32 v0, v190, v1
	s_waitcnt vmcnt(6)
	v_lshlrev_b32_e32 v2, 16, v214
	v_cvt_pk_bf16_f32 v0, v0, s0
	global_store_short v[198:199], v0, off
	v_mul_f32_e32 v0, v192, v2
	s_waitcnt vmcnt(6)
	v_lshlrev_b32_e32 v3, 16, v215
	v_cvt_pk_bf16_f32 v0, v0, s0
	global_store_short v[200:201], v0, off
	v_mul_f32_e32 v0, v194, v3
	v_cvt_pk_bf16_f32 v0, v0, s0
	global_store_short v[202:203], v0, off
	ds_read_b32 v1, v134 offset:51200
	ds_read_b32 v2, v135
	ds_read_b32 v3, v136 offset:51200
	ds_read_b32 v8, v137
	ds_read_b32 v9, v138 offset:51200
	ds_read_b32 v10, v139
	ds_read_b32 v11, v140 offset:51200
	ds_read_b32 v0, v141
	s_waitcnt vmcnt(7)
	v_lshlrev_b32_e32 v4, 16, v216
	s_waitcnt lgkmcnt(6)
	v_fmac_f32_e32 v2, v1, v194
	v_mul_f32_e32 v1, v2, v4
	s_waitcnt vmcnt(6)
	v_lshlrev_b32_e32 v5, 16, v217
	v_cvt_pk_bf16_f32 v1, v1, s0
	s_waitcnt lgkmcnt(4)
	v_fmac_f32_e32 v8, v3, v2
	global_store_short v[204:205], v1, off
	v_mul_f32_e32 v1, v8, v5
	s_waitcnt vmcnt(6)
	v_lshlrev_b32_e32 v6, 16, v218
	v_cvt_pk_bf16_f32 v1, v1, s0
	s_waitcnt lgkmcnt(2)
	v_fmac_f32_e32 v10, v9, v8
	global_store_short v[206:207], v1, off
	v_mul_f32_e32 v1, v10, v6
	s_waitcnt vmcnt(6)
	v_lshlrev_b32_e32 v7, 16, v219
	v_cvt_pk_bf16_f32 v1, v1, s0
	s_waitcnt lgkmcnt(0)
	v_fmac_f32_e32 v0, v11, v10
	global_store_short v[208:209], v1, off
	v_mul_f32_e32 v1, v0, v7
	v_cvt_pk_bf16_f32 v1, v1, s0
	global_store_short v[210:211], v1, off
	s_cbranch_vccnz .LBB0_1683
	s_and_saveexec_b64 s[4:5], s[8:9]
	s_cbranch_execnz .LBB0_1685
	s_or_b64 exec, exec, s[4:5]
	s_and_saveexec_b64 s[4:5], s[10:11]
	s_cbranch_execnz .LBB0_1686

; #define RG_RAW_LOAD(tile_) do { _Pragma("unroll") for (int i = 0; i < 5; ++i) { const int q = tid + 512 * i, row = q >> 4, c16 = q & 15, tl = (tile_) * 128 - 3 + row; \
;         pre[i] = (q < 131 * 16 && tl >= 0) ? *(const u32x4*)(XR + ((size_t)b * SEQ + tl) * D + cb0 + c16 * 8) : (u32x4){0u, 0u, 0u, 0u}; } } while (0)
; #define RG_RAW_STORE() do { _Pragma("unroll") for (int i = 0; i < 5; ++i) { const int q = tid + 512 * i; if (q < 131 * 16) *(LAS u32x4*)(rawt + (q >> 4) * 136 + (q & 15) * 8) = pre[i]; } } while (0)
; __device__ __forceinline__ void rglru_task(const Params& P, LAS unsigned char* lds, int b, int n, int qd, int tid, int t0, int t1) {
;     ...
;     if (prompt) { RG_RAW_LOAD(t0); RG_RAW_STORE(); }
.LBB0_1706:
	s_or_b64 exec, exec, s[14:15]
	s_lshl_b32 s7, s56, 17
	s_add_u32 s7, s10, s7
	s_addc_u32 s10, s11, 0
	s_lshl_b64 s[8:9], s[12:13], 1
	v_lshlrev_b32_e32 v2, 3, v0
	s_add_u32 s8, s7, s8
	v_and_b32_e32 v2, 0x78, v2
	s_addc_u32 s9, s10, s9
	v_lshlrev_b32_e32 v48, 1, v2
	v_lshl_add_u64 v[4:5], s[8:9], 0, v[48:49]
	s_mov_b64 s[8:9], 0x5040000
	s_movk_i32 s7, 0x830
	v_lshl_add_u64 v[74:75], v[4:5], 0, s[8:9]
	v_ashrrev_i32_e32 v79, 4, v0
	v_cmp_gt_i32_e64 s[8:9], s7, v0
	s_movk_i32 s7, 0xfc82
	v_cmp_lt_i32_e64 s[10:11], s7, v79
	s_and_b64 s[12:13], s[8:9], s[10:11]
	v_mov_b32_e32 v48, v49
	v_mov_b32_e32 v50, v49
	v_mov_b32_e32 v51, v49
	s_and_saveexec_b64 s[10:11], s[12:13]
	s_cbranch_execz .LBB0_1708
	v_add_u32_e32 v4, 0x1fd, v79
	v_mov_b32_e32 v5, 0
	v_lshlrev_b64 v[4:5], 11, v[4:5]
	v_lshl_add_u64 v[4:5], v[74:75], 0, v[4:5]
	global_load_dwordx4 v[48:51], v[4:5], off
.LBB0_1708:
	s_or_b64 exec, exec, s[10:11]
	v_add_u32_e32 v3, 0x200, v0
	v_mov_b32_e32 v56, 0
	v_ashrrev_i32_e32 v80, 4, v3
	s_movk_i32 s10, 0x630
	v_mov_b32_e32 v57, v56
	v_cmp_gt_i32_e64 s[10:11], s10, v0
	v_cmp_lt_i32_e64 s[12:13], s7, v80
	v_mov_b32_e32 v58, v56
	v_mov_b32_e32 v59, v56
	v_mov_b64_e32 v[52:53], v[56:57]
	s_and_b64 s[14:15], s[10:11], s[12:13]
	v_mov_b64_e32 v[54:55], v[58:59]
	s_and_saveexec_b64 s[12:13], s[14:15]
	s_cbranch_execz .LBB0_1710
	v_add_u32_e32 v4, 0x1fd, v80
	v_mov_b32_e32 v5, v56
	v_lshlrev_b64 v[4:5], 11, v[4:5]
	v_lshl_add_u64 v[4:5], v[74:75], 0, v[4:5]
	global_load_dwordx4 v[52:55], v[4:5], off
.LBB0_1710:
	s_or_b64 exec, exec, s[12:13]
	v_add_u32_e32 v3, 0x400, v0
	s_movk_i32 s7, 0x430
	v_ashrrev_i32_e32 v81, 4, v3
	v_cmp_gt_i32_e64 s[12:13], s7, v0
	s_movk_i32 s7, 0xfc82
	v_cmp_lt_i32_e64 s[14:15], s7, v81
	s_and_b64 s[16:17], s[12:13], s[14:15]
	s_and_saveexec_b64 s[14:15], s[16:17]
	s_cbranch_execz .LBB0_1712
	v_add_u32_e32 v4, 0x1fd, v81
	v_mov_b32_e32 v5, 0
	v_lshlrev_b64 v[4:5], 11, v[4:5]
	v_lshl_add_u64 v[4:5], v[74:75], 0, v[4:5]
	global_load_dwordx4 v[56:59], v[4:5], off
.LBB0_1712:
	s_or_b64 exec, exec, s[14:15]
	v_add_u32_e32 v3, 0x600, v0
	v_mov_b32_e32 v64, 0
	v_ashrrev_i32_e32 v82, 4, v3
	s_movk_i32 s14, 0x230
	v_mov_b32_e32 v65, v64
	v_cmp_gt_i32_e64 s[14:15], s14, v0
	v_cmp_lt_i32_e64 s[16:17], s7, v82
	v_mov_b32_e32 v66, v64
	v_mov_b32_e32 v67, v64
	v_mov_b64_e32 v[60:61], v[64:65]
	s_and_b64 s[18:19], s[14:15], s[16:17]
	v_mov_b64_e32 v[62:63], v[66:67]
	s_and_saveexec_b64 s[16:17], s[18:19]
	s_cbranch_execz .LBB0_1714
	v_add_u32_e32 v4, 0x1fd, v82
	v_mov_b32_e32 v5, 0
	v_lshlrev_b64 v[4:5], 11, v[4:5]
	v_lshl_add_u64 v[4:5], v[74:75], 0, v[4:5]
	global_load_dwordx4 v[60:63], v[4:5], off

; #define LAS __attribute__((address_space(3)))
; __device__ __forceinline__ float softplus_f(float x) { return x > 20.f ? x : log1pf(__expf(x)); }
; __device__ __forceinline__ unsigned char* karg_ws() { return *(volatile KAS ucptr_t*)((const KAS char*)__builtin_amdgcn_kernarg_segment_ptr() + 264); }
; #define INP(k) karg_in(k)
; #define RG_RAW_LOAD(tile_) do { _Pragma("unroll") for (int i = 0; i < 5; ++i) { const int q = tid + 512 * i, row = q >> 4, c16 = q & 15, tl = (tile_) * 128 - 3 + row; \
;         pre[i] = (q < 131 * 16 && tl >= 0) ? *(const u32x4*)(XR + ((size_t)b * SEQ + tl) * D + cb0 + c16 * 8) : (u32x4){0u, 0u, 0u, 0u}; } } while (0)
; #define lane opq(lane_now())
; __device__ __forceinline__ void rglru_task(const Params& P, LAS unsigned char* lds, int b, int n, int qd, int tid, int t0, int t1) {
;     const int lane = tid & 63, wave = tid >> 6;
;     LAS bf16* xcA = (LAS bf16*)lds;
;     LAS float* xcf = (LAS float*)(lds + 34816);
;     LAS float* rb = (LAS float*)(lds + 51200);
;     LAS float* ib = (LAS float*)(lds + 67584);
;     LAS float* segA = (LAS float*)(lds + 83968);
;     LAS float* segB = (LAS float*)(lds + 86016);
;     LAS float* hc = (LAS float*)(lds + 88064);
;     LAS float* cw = (LAS float*)(lds + 88192);
;     LAS bf16* rawt = (LAS bf16*)(lds + 90752);
;     bf16* XR = (bf16*)(karg_ws() + WS_Z); bf16* GR = (bf16*)(karg_ws() + WS_Z + ZB);
;     const bf16* WRG = (const bf16*)(karg_ws() + WS_WRG);
;     const int cb0 = n * 128, oc0 = cb0 + qd * 32;
;     const bool prompt = b >= 0;
;     for (int i = tid; i < 640; i += NTHR) cw[i] = i < 512 ? INP(15)[(size_t)(i >> 7) * D + cb0 + (i & 127)] : INP(16)[cb0 + (i - 512)];
;     if (tid < 32) hc[tid] = t0 > 0 ? ((const float*)(karg_ws() + WS_HCARRY))[(size_t)b * D + oc0 + tid] : 0.f;
;     const int tb = wave & 3, cbk = wave >> 2;
;     bf16x8 Bf[8];
;     { const bf16* wrow = WRG + (size_t)(n * 256 + cbk * 128 + qd * 32 + (lane & 31)) * 128 + (lane >> 5) * 8;
; #pragma unroll
;       for (int ks = 0; ks < 8; ++ks) Bf[ks] = *(const bf16x8*)(wrow + ks * 16); }
;     const float gbias = INP(cbk ? 20 : 18)[oc0 + (lane & 31)];
;     const int ch = tid & 31, seg = tid >> 5;
;     const float sp = softplus_f(-INP(21)[oc0 + ch]);
;     float hlast = 0.f;
;     u32x4 pre[5];
;     ...
;     if (prompt) { RG_RAW_LOAD(t0); RG_RAW_STORE(); }
;     __syncthreads();
;     const int ntiles = t1;
.LBB0_1722:
	s_or_b64 exec, exec, s[18:19]
	v_lshrrev_b32_e32 v4, 1, v0
	s_mov_b32 s7, 0
	v_and_b32_e32 v8, 3, v0
	v_and_b32_e32 v10, 0x60, v4
	s_lshl_b32 s61, s56, 6
	v_cmp_eq_u32_e64 s[18:19], s3, v8
	v_or_b32_e32 v4, v10, v72
	s_add_i32 s3, 0, 0xc800
	s_lshl_b64 s[20:21], s[6:7], 1
	v_mul_u32_u24_e32 v11, 0x110, v4
	v_mov_b32_e32 v4, s57
	v_mov_b32_e32 v5, s3
	v_mov_b32_e32 v68, 0
	s_add_u32 s4, s4, s20
	v_cndmask_b32_e32 v12, v4, v5, vcc
	s_addc_u32 s5, s5, s21
	v_lshlrev_b32_e32 v4, 1, v72
	v_mov_b32_e32 v5, v68
	v_lshlrev_b32_e32 v13, 2, v72
	v_lshl_add_u64 v[4:5], s[4:5], 0, v[4:5]
	s_mov_b64 s[4:5], 0x7080000
	v_lshl_add_u64 v[76:77], v[4:5], 0, s[4:5]
	v_or_b32_e32 v4, 0x80, v13
	v_add_u32_e32 v89, s58, v4
	v_add_u32_e32 v90, s59, v4
	v_or_b32_e32 v4, 0x100, v13
	v_add_u32_e32 v91, s58, v4
	v_add_u32_e32 v92, s59, v4
	v_or_b32_e32 v4, 0x180, v13
	v_add_u32_e32 v93, s58, v4
	v_add_u32_e32 v94, s59, v4
	v_or_b32_e32 v4, 0x200, v13
	v_add_u32_e32 v95, s58, v4
	v_add_u32_e32 v96, s59, v4
	v_or_b32_e32 v4, 0x280, v13
	v_add_u32_e32 v97, s58, v4
	v_add_u32_e32 v98, s59, v4
	v_or_b32_e32 v4, 0x300, v13
	v_add_u32_e32 v99, s58, v4
	v_add_u32_e32 v100, s59, v4
	v_or_b32_e32 v4, 0x380, v13
	v_add_u32_e32 v101, s58, v4
	v_add_u32_e32 v102, s59, v4
	v_or_b32_e32 v4, 0x400, v13
	v_add_u32_e32 v103, s58, v4
	v_add_u32_e32 v104, s59, v4
	v_or_b32_e32 v4, 0x480, v13
	v_add_u32_e32 v105, s58, v4
	v_add_u32_e32 v106, s59, v4
	v_or_b32_e32 v4, 0x500, v13
	v_add_u32_e32 v107, s58, v4
	v_add_u32_e32 v108, s59, v4
	v_or_b32_e32 v4, 0x580, v13
	v_add_u32_e32 v109, s58, v4
	v_add_u32_e32 v110, s59, v4
	v_or_b32_e32 v4, 0x600, v13
	v_ashrrev_i32_e32 v6, 5, v0
	v_add_u32_e32 v111, s58, v4
	v_add_u32_e32 v112, s59, v4
	v_or_b32_e32 v4, 0x680, v13
	v_lshlrev_b32_e32 v85, 3, v6
	v_add_u32_e32 v113, s58, v4
	v_add_u32_e32 v114, s59, v4
	v_or_b32_e32 v4, 0x700, v13
	v_add_u32_e32 v115, s58, v4
	v_add_u32_e32 v116, s59, v4
	v_or_b32_e32 v119, 1, v85
	v_lshl_or_b32 v4, v6, 10, v13
	v_or_b32_e32 v120, 2, v85
	v_add_u32_e32 v126, 0, v4
	v_add_u32_e32 v127, s57, v4
	v_lshl_or_b32 v4, v119, 7, v13
	v_or_b32_e32 v121, 3, v85
	v_add_u32_e32 v128, 0, v4
	v_add_u32_e32 v129, s57, v4
	v_lshl_or_b32 v4, v120, 7, v13
	v_or_b32_e32 v122, 4, v85
	v_add_u32_e32 v130, 0, v4
	v_add_u32_e32 v131, s57, v4
	v_lshl_or_b32 v4, v121, 7, v13
	v_or_b32_e32 v123, 5, v85
	v_add_u32_e32 v132, 0, v4
	v_add_u32_e32 v133, s57, v4
	v_lshl_or_b32 v4, v122, 7, v13
	v_or_b32_e32 v124, 6, v85
	v_add_u32_e32 v134, 0, v4
	v_add_u32_e32 v135, s57, v4
	v_lshl_or_b32 v4, v123, 7, v13
	v_ashrrev_i32_e32 v7, 2, v0
	v_lshlrev_b32_e32 v0, 2, v0
	v_or_b32_e32 v125, 7, v85
	v_add_u32_e32 v136, 0, v4
	v_add_u32_e32 v137, s57, v4
	v_lshl_or_b32 v4, v124, 7, v13
	v_add_u32_e32 v86, s58, v0
	v_add_u32_e32 v87, s59, v0
	v_lshlrev_b32_e32 v0, 9, v1
	v_add_u32_e32 v138, 0, v4
	v_add_u32_e32 v139, s57, v4
	v_lshl_or_b32 v4, v125, 7, v13
	v_lshl_add_u32 v3, v3, 1, 0
	v_mul_lo_u32 v9, v7, s54
	v_cmp_eq_u32_e64 s[20:21], 15, v6
	v_lshlrev_b32_e32 v1, 7, v10
	v_add3_u32 v0, v12, v13, v0
	v_cmp_lt_i32_e64 s[22:23], 0, v6
	v_cmp_lt_i32_e64 s[24:25], 1, v6
	v_cmp_lt_i32_e64 s[26:27], 2, v6
	v_cmp_lt_i32_e64 s[28:29], 3, v6
	v_cmp_lt_i32_e64 s[30:31], 4, v6
	v_cmp_lt_i32_e64 s[34:35], 5, v6
	v_cmp_lt_i32_e64 s[36:37], 6, v6
	v_cmp_lt_i32_e64 s[38:39], 7, v6
	v_cmp_lt_i32_e64 s[40:41], 8, v6
	v_cmp_lt_i32_e64 s[42:43], 9, v6
	v_cmp_lt_i32_e64 s[44:45], 10, v6
	v_cmp_lt_i32_e64 s[46:47], 11, v6
	v_cmp_lt_i32_e64 s[48:49], 12, v6
	v_cmp_lt_i32_e64 s[50:51], 13, v6
	v_cmp_lt_i32_e64 s[52:53], 14, v6
	v_add_u32_e32 v140, 0, v4
	v_add_u32_e32 v141, s57, v4
	v_mul_lo_u32 v4, v79, s54
	v_mul_lo_u32 v5, v80, s54
	v_mul_lo_u32 v6, v81, s54
	v_mul_lo_u32 v10, v82, s54
	v_mov_b32_e32 v12, 0x8800
	v_add_u32_e32 v88, s63, v13
	s_mov_b32 s65, 4
	v_add_u32_e32 v117, s59, v13
	v_add_u32_e32 v118, s58, v13
	v_lshlrev_b32_e32 v142, 7, v8
	v_lshl_add_u32 v143, v7, 7, v12
	v_lshl_add_u32 v144, v8, 6, v9
	v_add_u32_e32 v145, v3, v11
	v_add_u32_e32 v146, v0, v1
	v_mov_b32_e32 v147, 0x3c088889
	s_mov_b32 s3, 0xbe99999a
	v_add_u32_e32 v148, v2, v4
	v_add_u32_e32 v149, v2, v5
	v_add_u32_e32 v150, v2, v6
	v_add_u32_e32 v151, v2, v10
	s_waitcnt lgkmcnt(0)
	s_barrier
	s_branch .LBB0_1724

; #define INP(k) karg_in(k)
; #define RG_RAW_LOAD(tile_) do { _Pragma("unroll") for (int i = 0; i < 5; ++i) { const int q = tid + 512 * i, row = q >> 4, c16 = q & 15, tl = (tile_) * 128 - 3 + row; \
;         pre[i] = (q < 131 * 16 && tl >= 0) ? *(const u32x4*)(XR + ((size_t)b * SEQ + tl) * D + cb0 + c16 * 8) : (u32x4){0u, 0u, 0u, 0u}; } } while (0)
; __device__ __forceinline__ void rglru_task(const Params& P, LAS unsigned char* lds, int b, int n, int qd, int tid, int t0, int t1) {
;     ...
;     for (int tile = t0; tile < ntiles; ++tile) {
;         const int row0 = prompt ? b * SEQ + tile * 128 : MPR;
;         if (prompt && tile + 1 < ntiles) RG_RAW_LOAD(tile + 1);
;     ...
;         { float gr[8], h0v[8];
; #pragma unroll
;           for (int e = 0; e < 8; ++e) { const int t = seg * 8 + e; gr[e] = bf2f(GR[(size_t)(row0 + t) * D + oc0 + ch]); h0v[e] = prompt ? 0.f : INP(4)[(size_t)t * D + oc0 + ch]; }
.LBB0_1736:
	s_lshl_b32 s32, s65, 7
	s_add_i32 s32, s32, s61
	v_add_u32_e32 v196, s32, v85
	v_ashrrev_i32_e32 v197, 31, v196
	v_add_u32_e32 v198, s32, v119
	v_add_u32_e32 v200, s32, v120
	v_add_u32_e32 v202, s32, v121
	v_add_u32_e32 v204, s32, v122
	v_add_u32_e32 v206, s32, v123
	v_add_u32_e32 v208, s32, v124
	v_add_u32_e32 v210, s32, v125
	v_lshlrev_b64 v[196:197], 11, v[196:197]
	v_ashrrev_i32_e32 v199, 31, v198
	v_ashrrev_i32_e32 v201, 31, v200
	v_ashrrev_i32_e32 v203, 31, v202
	v_ashrrev_i32_e32 v205, 31, v204
	v_ashrrev_i32_e32 v207, 31, v206
	v_ashrrev_i32_e32 v209, 31, v208
	v_ashrrev_i32_e32 v211, 31, v210
	v_lshl_add_u64 v[196:197], v[76:77], 0, v[196:197]
	v_lshlrev_b64 v[198:199], 11, v[198:199]
	v_lshlrev_b64 v[200:201], 11, v[200:201]
	v_lshlrev_b64 v[202:203], 11, v[202:203]
	v_lshlrev_b64 v[204:205], 11, v[204:205]
	v_lshlrev_b64 v[206:207], 11, v[206:207]
	v_lshlrev_b64 v[208:209], 11, v[208:209]
	v_lshlrev_b64 v[210:211], 11, v[210:211]
	v_lshl_add_u64 v[198:199], v[76:77], 0, v[198:199]
	v_lshl_add_u64 v[200:201], v[76:77], 0, v[200:201]
	v_lshl_add_u64 v[202:203], v[76:77], 0, v[202:203]
	v_lshl_add_u64 v[204:205], v[76:77], 0, v[204:205]
	v_lshl_add_u64 v[206:207], v[76:77], 0, v[206:207]
	v_lshl_add_u64 v[208:209], v[76:77], 0, v[208:209]
	v_lshl_add_u64 v[210:211], v[76:77], 0, v[210:211]
	global_load_ushort v212, v[196:197], off
	global_load_ushort v213, v[198:199], off
	global_load_ushort v214, v[200:201], off
	global_load_ushort v215, v[202:203], off
	global_load_ushort v216, v[204:205], off
	global_load_ushort v217, v[206:207], off
	global_load_ushort v218, v[208:209], off
	global_load_ushort v219, v[210:211], off
	s_mov_b32 s54, 4
	v_mov_b32_e32 v8, v144
	v_mov_b32_e32 v9, v143
	v_mov_b32_e32 v10, v142
	s_branch .LBB0_1738

; __device__ __forceinline__ unsigned f2bf(float f) { return pk2(f, f) & 0xffffu; }
; __device__ __forceinline__ float* karg_out() { return *(volatile KAS fptr_t*)((const KAS char*)__builtin_amdgcn_kernarg_segment_ptr() + 256); }
; #define INP(k) karg_in(k)
; __device__ __forceinline__ void rglru_task(const Params& P, LAS unsigned char* lds, int b, int n, int qd, int tid, int t0, int t1) {
;     ...
;         float hin = 0.f;
;         if (prompt) {
;             segA[seg * 32 + ch] = Aacc; segB[seg * 32 + ch] = h;
;             __syncthreads();
;             hin = hc[ch];
;             float sa[15], sb[15];
; #pragma unroll
;             for (int s = 0; s < 15; ++s) { sa[s] = segA[s * 32 + ch]; sb[s] = segB[s * 32 + ch]; }
; #pragma unroll
;             for (int s = 0; s < 15; ++s) hin = s < seg ? sa[s] * hin + sb[s] : hin;
;         }
;         h = hin;
;         { float gr[8], h0v[8];
; #pragma unroll
;           for (int e = 0; e < 8; ++e) { const int t = seg * 8 + e; gr[e] = bf2f(GR[(size_t)(row0 + t) * D + oc0 + ch]); h0v[e] = prompt ? 0.f : INP(4)[(size_t)t * D + oc0 + ch]; }
; #pragma unroll
;           for (int e = 0; e < 8; ++e) { const int t = seg * 8 + e;
;               const float a = rb[t * 32 + ch], bt = ib[t * 32 + ch];
;               if (prompt) h = a * h + bt; else h = a * h0v[e] + bt;
;               GR[(size_t)(row0 + t) * D + oc0 + ch] = (bf16)f2bf(h * gr[e]);
;               if (!prompt) { karg_out()[O_HS + (size_t)t * D + oc0 + ch] = h;
;                   const float* cs = INP(5) + (size_t)t * 3 * D + oc0 + ch; float* co = karg_out() + O_CRS + (size_t)t * 3 * D + oc0 + ch;
;                   co[0] = cs[D]; co[D] = cs[2 * D]; co[2 * D] = bf2f(XR[(size_t)(MPR + t) * D + oc0 + ch]); }
;           } }
;         hlast = h;
.LBB0_1746:
	s_or_b64 exec, exec, s[4:5]
	s_waitcnt lgkmcnt(14)
	v_fmac_f32_e32 v14, v161, v0
	v_cndmask_b32_e64 v0, v0, v14, s[24:25]
	v_fmac_f32_e32 v15, v1, v0
	v_cndmask_b32_e64 v0, v0, v15, s[26:27]
	v_fmac_f32_e32 v69, v2, v0
	v_cndmask_b32_e64 v0, v0, v69, s[28:29]
	v_fmac_f32_e32 v70, v3, v0
	v_cndmask_b32_e64 v0, v0, v70, s[30:31]
	v_fmac_f32_e32 v71, v4, v0
	v_cndmask_b32_e64 v0, v0, v71, s[34:35]
	v_fmac_f32_e32 v152, v5, v0
	v_cndmask_b32_e64 v0, v0, v152, s[36:37]
	v_fmac_f32_e32 v153, v6, v0
	v_cndmask_b32_e64 v0, v0, v153, s[38:39]
	s_waitcnt lgkmcnt(12)
	v_fmac_f32_e32 v154, v7, v0
	v_cndmask_b32_e64 v0, v0, v154, s[40:41]
	s_waitcnt lgkmcnt(10)
	v_fmac_f32_e32 v155, v8, v0
	v_cndmask_b32_e64 v0, v0, v155, s[42:43]
	s_waitcnt lgkmcnt(8)
	v_fmac_f32_e32 v156, v9, v0
	v_cndmask_b32_e64 v0, v0, v156, s[44:45]
	s_waitcnt lgkmcnt(6)
	v_fmac_f32_e32 v157, v10, v0
	v_cndmask_b32_e64 v0, v0, v157, s[46:47]
	s_waitcnt lgkmcnt(4)
	v_fmac_f32_e32 v158, v11, v0
	v_cndmask_b32_e64 v0, v0, v158, s[48:49]
	s_waitcnt lgkmcnt(2)
	v_fmac_f32_e32 v159, v12, v0
	v_cndmask_b32_e64 v0, v0, v159, s[50:51]
	s_waitcnt lgkmcnt(0)
	v_fmac_f32_e32 v160, v13, v0
	ds_read_b32 v161, v126 offset:51200
	ds_read_b32 v188, v127
	ds_read_b32 v189, v128 offset:51200
	ds_read_b32 v190, v129
	ds_read_b32 v191, v130 offset:51200
	ds_read_b32 v192, v131
	ds_read_b32 v193, v132 offset:51200
	ds_read_b32 v194, v133
	v_cndmask_b32_e64 v0, v0, v160, s[52:53]
	s_waitcnt lgkmcnt(6)
	v_fmac_f32_e32 v188, v161, v0
	s_waitcnt lgkmcnt(4)
	v_fmac_f32_e32 v190, v189, v188
	s_waitcnt lgkmcnt(2)
	v_fmac_f32_e32 v192, v191, v190
	s_waitcnt lgkmcnt(0)
	v_fmac_f32_e32 v194, v193, v192
	s_andn2_b64 vcc, exec, s[62:63]
	s_waitcnt vmcnt(7)
	v_lshlrev_b32_e32 v0, 16, v212
	v_mul_f32_e32 v0, v188, v0
	s_waitcnt vmcnt(6)
	v_lshlrev_b32_e32 v1, 16, v213
	v_cvt_pk_bf16_f32 v0, v0, s0
	global_store_short v[196:197], v0, off
	v_mul_f32_e32 v0, v190, v1
	s_waitcnt vmcnt(6)
	v_lshlrev_b32_e32 v2, 16, v214
	v_cvt_pk_bf16_f32 v0, v0, s0
	global_store_short v[198:199], v0, off
	v_mul_f32_e32 v0, v192, v2
	s_waitcnt vmcnt(6)
	v_lshlrev_b32_e32 v3, 16, v215
	v_cvt_pk_bf16_f32 v0, v0, s0
	global_store_short v[200:201], v0, off
	v_mul_f32_e32 v0, v194, v3
	v_cvt_pk_bf16_f32 v0, v0, s0
	global_store_short v[202:203], v0, off
	ds_read_b32 v1, v134 offset:51200
	ds_read_b32 v2, v135
	ds_read_b32 v3, v136 offset:51200
	ds_read_b32 v8, v137
	ds_read_b32 v9, v138 offset:51200
	ds_read_b32 v10, v139
	ds_read_b32 v11, v140 offset:51200
	ds_read_b32 v0, v141
	s_waitcnt vmcnt(7)
	v_lshlrev_b32_e32 v4, 16, v216
	s_waitcnt lgkmcnt(6)
	v_fmac_f32_e32 v2, v1, v194
	v_mul_f32_e32 v1, v2, v4
	s_waitcnt vmcnt(6)
	v_lshlrev_b32_e32 v5, 16, v217
	v_cvt_pk_bf16_f32 v1, v1, s0
	s_waitcnt lgkmcnt(4)
	v_fmac_f32_e32 v8, v3, v2
	global_store_short v[204:205], v1, off
	v_mul_f32_e32 v1, v8, v5
	s_waitcnt vmcnt(6)
	v_lshlrev_b32_e32 v6, 16, v218
	v_cvt_pk_bf16_f32 v1, v1, s0
	s_waitcnt lgkmcnt(2)
	v_fmac_f32_e32 v10, v9, v8
	global_store_short v[206:207], v1, off
	v_mul_f32_e32 v1, v10, v6
	s_waitcnt vmcnt(6)
	v_lshlrev_b32_e32 v7, 16, v219
	v_cvt_pk_bf16_f32 v1, v1, s0
	s_waitcnt lgkmcnt(0)
	v_fmac_f32_e32 v0, v11, v10
	global_store_short v[208:209], v1, off
	v_mul_f32_e32 v1, v0, v7
	v_cvt_pk_bf16_f32 v1, v1, s0
	global_store_short v[210:211], v1, off
	s_cbranch_vccnz .LBB0_1754
	s_and_saveexec_b64 s[4:5], s[8:9]
	s_cbranch_execnz .LBB0_1756
	s_or_b64 exec, exec, s[4:5]
	s_and_saveexec_b64 s[4:5], s[10:11]
	s_cbranch_execnz .LBB0_1757

; #define RG_RAW_LOAD(tile_) do { _Pragma("unroll") for (int i = 0; i < 5; ++i) { const int q = tid + 512 * i, row = q >> 4, c16 = q & 15, tl = (tile_) * 128 - 3 + row; \
;         pre[i] = (q < 131 * 16 && tl >= 0) ? *(const u32x4*)(XR + ((size_t)b * SEQ + tl) * D + cb0 + c16 * 8) : (u32x4){0u, 0u, 0u, 0u}; } } while (0)
; #define RG_RAW_STORE() do { _Pragma("unroll") for (int i = 0; i < 5; ++i) { const int q = tid + 512 * i; if (q < 131 * 16) *(LAS u32x4*)(rawt + (q >> 4) * 136 + (q & 15) * 8) = pre[i]; } } while (0)
; __device__ __forceinline__ void rglru_task(const Params& P, LAS unsigned char* lds, int b, int n, int qd, int tid, int t0, int t1) {
;     ...
;     if (prompt) { RG_RAW_LOAD(t0); RG_RAW_STORE(); }
.LBB0_1879:
	v_add_u32_e32 v4, 0x1fd, v83
	v_mov_b32_e32 v5, 0
	v_lshlrev_b64 v[4:5], 11, v[4:5]
	v_lshl_add_u64 v[4:5], v[74:75], 0, v[4:5]
	global_load_dwordx4 v[64:67], v[4:5], off
	s_or_b64 exec, exec, s[18:19]
	v_lshl_add_u32 v2, v2, 1, s62
	s_and_saveexec_b64 s[18:19], s[8:9]
	s_cbranch_execz .LBB0_1716
